# attention steady loop: 3 PV MFMAs issued in the mid-step (DMA + row-max) section, K/V DMA addresses from SGPR bases, no self-max canonicalisation
# speedup vs baseline: 1.0094x; 1.0094x over previous
.LBB0_217:
	ds_read_b128 v[154:157], v149
	ds_read_b128 v[158:161], v149 offset:1024
	ds_read_b128 v[162:165], v149 offset:2048
	ds_read_b128 v[166:169], v149 offset:3072
	ds_read_b128 v[170:173], v150
	ds_read_b128 v[174:177], v150 offset:1024
	ds_read_b128 v[178:181], v150 offset:2048
	ds_read_b128 v[182:185], v150 offset:3072
	s_add_u32 s0, s48, 0xfffc0080
	s_addc_u32 s1, s49, -1
	s_cmp_eq_u32 s62, 12
	s_cselect_b32 s55, s24, s1
	s_cselect_b32 s54, s25, s0
	s_cselect_b32 s1, s15, s57
	s_cselect_b32 s0, s31, s56
	v_lshl_add_u64 v[218:219], s[48:49], 0, v[136:137]
	s_add_i32 m0, s26, 0xc000
	ds_read_b128 v[186:189], v151
	ds_read_b128 v[190:193], v151 offset:1024
	ds_read_b128 v[194:197], v151 offset:2048
	ds_read_b128 v[198:201], v151 offset:3072
	ds_read_b128 v[202:205], v151 offset:4096
	ds_read_b128 v[206:209], v151 offset:5120
	ds_read_b128 v[210:213], v151 offset:6144
	ds_read_b128 v[214:217], v151 offset:7168
	global_load_lds_dwordx4 v[218:219], off
	v_lshl_add_u64 v[218:219], s[48:49], 0, v[138:139]
	s_add_i32 m0, s26, 0xe000
	s_nop 0
	global_load_lds_dwordx4 v[218:219], off
	s_waitcnt vmcnt(8)
	s_waitcnt lgkmcnt(0)
	s_barrier
	s_setprio 1
	s_waitcnt lgkmcnt(0)
	v_mfma_f32_16x16x32_bf16 v[124:127], v[154:157], v[186:189], v[124:127]
	v_mfma_f32_16x16x32_bf16 v[120:123], v[162:165], v[186:189], v[120:123]
	v_mfma_f32_16x16x32_bf16 v[112:115], v[154:157], v[194:197], v[112:115]
	v_mfma_f32_16x16x32_bf16 v[104:107], v[162:165], v[194:197], v[104:107]
	v_mfma_f32_16x16x32_bf16 v[96:99], v[154:157], v[202:205], v[96:99]
	v_mfma_f32_16x16x32_bf16 v[88:91], v[162:165], v[202:205], v[88:91]
	v_mfma_f32_16x16x32_bf16 v[80:83], v[154:157], v[210:213], v[80:83]
	v_mfma_f32_16x16x32_bf16 v[72:75], v[162:165], v[210:213], v[72:75]
	v_mfma_f32_16x16x32_bf16 v[124:127], v[158:161], v[190:193], v[124:127]
	v_mfma_f32_16x16x32_bf16 v[120:123], v[166:169], v[190:193], v[120:123]
	v_mfma_f32_16x16x32_bf16 v[112:115], v[158:161], v[198:201], v[112:115]
	v_mfma_f32_16x16x32_bf16 v[104:107], v[166:169], v[198:201], v[104:107]
	v_mfma_f32_16x16x32_bf16 v[96:99], v[158:161], v[206:209], v[96:99]
	v_mfma_f32_16x16x32_bf16 v[88:91], v[166:169], v[206:209], v[88:91]
	v_mfma_f32_16x16x32_bf16 v[80:83], v[158:161], v[214:217], v[80:83]
	v_mfma_f32_16x16x32_bf16 v[72:75], v[166:169], v[214:217], v[72:75]
	s_setprio 0
	s_setprio 1
	v_mfma_f32_16x16x32_bf16 v[116:119], v[170:173], v[186:189], v[116:119]
	v_mfma_f32_16x16x32_bf16 v[108:111], v[178:181], v[186:189], v[108:111]
	v_mfma_f32_16x16x32_bf16 v[100:103], v[170:173], v[194:197], v[100:103]
	v_mfma_f32_16x16x32_bf16 v[92:95], v[178:181], v[194:197], v[92:95]
	v_mfma_f32_16x16x32_bf16 v[84:87], v[170:173], v[202:205], v[84:87]
	v_mfma_f32_16x16x32_bf16 v[76:79], v[178:181], v[202:205], v[76:79]
	v_mfma_f32_16x16x32_bf16 v[68:71], v[170:173], v[210:213], v[68:71]
	v_mfma_f32_16x16x32_bf16 v[64:67], v[178:181], v[210:213], v[64:67]
	v_mfma_f32_16x16x32_bf16 v[116:119], v[174:177], v[190:193], v[116:119]
	v_mfma_f32_16x16x32_bf16 v[108:111], v[182:185], v[190:193], v[108:111]
	v_mfma_f32_16x16x32_bf16 v[100:103], v[174:177], v[198:201], v[100:103]
	v_mfma_f32_16x16x32_bf16 v[92:95], v[182:185], v[198:201], v[92:95]
	v_mfma_f32_16x16x32_bf16 v[84:87], v[174:177], v[206:209], v[84:87]
	v_mfma_f32_16x16x32_bf16 v[76:79], v[182:185], v[206:209], v[76:79]
	v_mfma_f32_16x16x32_bf16 v[68:71], v[174:177], v[214:217], v[68:71]
	v_mfma_f32_16x16x32_bf16 v[64:67], v[182:185], v[214:217], v[64:67]
	s_setprio 0
	s_barrier
	s_add_i32 s63, s47, s17
	v_lshl_add_u64 v[218:219], s[0:1], 0, v[132:133]
	s_mov_b32 m0, s63
	ds_read_b128 v[186:189], v151 offset:16384
	ds_read_b128 v[190:193], v151 offset:17408
	ds_read_b128 v[194:197], v151 offset:18432
	ds_read_b128 v[198:201], v151 offset:19456
	ds_read_b128 v[202:205], v151 offset:20480
	ds_read_b128 v[206:209], v151 offset:21504
	ds_read_b128 v[210:213], v151 offset:22528
	ds_read_b128 v[214:217], v151 offset:23552
	global_load_lds_dwordx4 v[218:219], off
	s_add_i32 m0, s63, 0x2000
	s_add_u32 s66, s0, 0x40000
	v_lshl_add_u64 v[220:221], s[0:1], 0, v[128:129]
	s_addc_u32 s67, s1, 0
	s_add_i32 s63, s50, s17
	global_load_lds_dwordx4 v[220:221], off
	v_lshl_add_u64 v[222:223], s[66:67], 0, v[132:133]
	s_mov_b32 m0, s63
	v_lshl_add_u64 v[224:225], s[54:55], 0, v[130:131]
	global_load_lds_dwordx4 v[222:223], off
	v_lshl_add_u64 v[222:223], s[66:67], 0, v[128:129]
	s_add_i32 m0, s63, 0x2000
	s_nop 0
	global_load_lds_dwordx4 v[222:223], off
	v_lshl_add_u64 v[222:223], s[54:55], 0, v[134:135]
	s_mov_b32 m0, s26
	s_nop 0
	global_load_lds_dwordx4 v[222:223], off
	s_mov_b32 m0, s27
	s_nop 0
	global_load_lds_dwordx4 v[224:225], off
	s_waitcnt vmcnt(8)
	s_waitcnt lgkmcnt(0)
	s_barrier
	s_setprio 1
	s_waitcnt lgkmcnt(0)
	v_mfma_f32_16x16x32_bf16 v[60:63], v[154:157], v[186:189], v[60:63]
	v_mfma_f32_16x16x32_bf16 v[56:59], v[162:165], v[186:189], v[56:59]
	v_mfma_f32_16x16x32_bf16 v[48:51], v[154:157], v[194:197], v[48:51]
	v_mfma_f32_16x16x32_bf16 v[40:43], v[162:165], v[194:197], v[40:43]
	v_mfma_f32_16x16x32_bf16 v[32:35], v[154:157], v[202:205], v[32:35]
	v_mfma_f32_16x16x32_bf16 v[24:27], v[162:165], v[202:205], v[24:27]
	v_mfma_f32_16x16x32_bf16 v[16:19], v[154:157], v[210:213], v[16:19]
	v_mfma_f32_16x16x32_bf16 v[8:11], v[162:165], v[210:213], v[8:11]
	v_mfma_f32_16x16x32_bf16 v[60:63], v[158:161], v[190:193], v[60:63]
	v_mfma_f32_16x16x32_bf16 v[56:59], v[166:169], v[190:193], v[56:59]
	v_mfma_f32_16x16x32_bf16 v[48:51], v[158:161], v[198:201], v[48:51]
	v_mfma_f32_16x16x32_bf16 v[40:43], v[166:169], v[198:201], v[40:43]
	v_mfma_f32_16x16x32_bf16 v[32:35], v[158:161], v[206:209], v[32:35]
	v_mfma_f32_16x16x32_bf16 v[24:27], v[166:169], v[206:209], v[24:27]
	v_mfma_f32_16x16x32_bf16 v[16:19], v[158:161], v[214:217], v[16:19]
	v_mfma_f32_16x16x32_bf16 v[8:11], v[166:169], v[214:217], v[8:11]
	s_setprio 0
	s_setprio 1
	v_mfma_f32_16x16x32_bf16 v[52:55], v[170:173], v[186:189], v[52:55]
	v_mfma_f32_16x16x32_bf16 v[44:47], v[178:181], v[186:189], v[44:47]
	v_mfma_f32_16x16x32_bf16 v[36:39], v[170:173], v[194:197], v[36:39]
	v_mfma_f32_16x16x32_bf16 v[28:31], v[178:181], v[194:197], v[28:31]
	v_mfma_f32_16x16x32_bf16 v[20:23], v[170:173], v[202:205], v[20:23]
	v_mfma_f32_16x16x32_bf16 v[12:15], v[178:181], v[202:205], v[12:15]
	v_mfma_f32_16x16x32_bf16 v[4:7], v[170:173], v[210:213], v[4:7]
	v_mfma_f32_16x16x32_bf16 v[0:3], v[178:181], v[210:213], v[0:3]
	v_mfma_f32_16x16x32_bf16 v[52:55], v[174:177], v[190:193], v[52:55]
	v_mfma_f32_16x16x32_bf16 v[44:47], v[182:185], v[190:193], v[44:47]
	v_mfma_f32_16x16x32_bf16 v[36:39], v[174:177], v[198:201], v[36:39]
	v_mfma_f32_16x16x32_bf16 v[28:31], v[182:185], v[198:201], v[28:31]
	v_mfma_f32_16x16x32_bf16 v[20:23], v[174:177], v[206:209], v[20:23]
	v_mfma_f32_16x16x32_bf16 v[12:15], v[182:185], v[206:209], v[12:15]
	v_mfma_f32_16x16x32_bf16 v[4:7], v[174:177], v[214:217], v[4:7]
	v_mfma_f32_16x16x32_bf16 v[0:3], v[182:185], v[214:217], v[0:3]
	s_setprio 0
	s_barrier
	s_add_i32 s63, 0, 0x18000
	v_add_u32_e32 v144, s63, v147
	s_add_i32 s66, 0, 0x1c000
	ds_read_b128 v[154:157], v144
	ds_read_b128 v[158:161], v144 offset:1024
	ds_read_b128 v[162:165], v144 offset:2048
	ds_read_b128 v[166:169], v144 offset:3072
	v_add_u32_e32 v144, s66, v147
	ds_read_b128 v[170:173], v144
	ds_read_b128 v[174:177], v144 offset:1024
	ds_read_b128 v[178:181], v144 offset:2048
	ds_read_b128 v[182:185], v144 offset:3072
	s_add_u32 s54, s54, 0x40000
	s_addc_u32 s55, s55, 0
	s_mov_b32 m0, s33
	v_lshl_add_u64 v[226:227], s[54:55], 0, v[134:135]
	ds_read_b128 v[186:189], v151 offset:32768
	ds_read_b128 v[190:193], v151 offset:33792
	ds_read_b128 v[194:197], v151 offset:34816
	ds_read_b128 v[198:201], v151 offset:35840
	ds_read_b128 v[202:205], v151 offset:36864
	ds_read_b128 v[206:209], v151 offset:37888
	ds_read_b128 v[210:213], v151 offset:38912
	ds_read_b128 v[214:217], v151 offset:39936
	global_load_lds_dwordx4 v[226:227], off
	v_lshl_add_u64 v[226:227], s[54:55], 0, v[130:131]
	s_mov_b32 m0, s34
	s_nop 0
	global_load_lds_dwordx4 v[226:227], off
	s_waitcnt vmcnt(8)
	s_waitcnt lgkmcnt(0)
	s_barrier
	s_setprio 1
	s_waitcnt lgkmcnt(0)
	v_mfma_f32_16x16x32_bf16 v[124:127], v[154:157], v[186:189], v[124:127]
	v_mfma_f32_16x16x32_bf16 v[120:123], v[162:165], v[186:189], v[120:123]
	v_mfma_f32_16x16x32_bf16 v[112:115], v[154:157], v[194:197], v[112:115]
	v_mfma_f32_16x16x32_bf16 v[104:107], v[162:165], v[194:197], v[104:107]
	v_mfma_f32_16x16x32_bf16 v[96:99], v[154:157], v[202:205], v[96:99]
	v_mfma_f32_16x16x32_bf16 v[88:91], v[162:165], v[202:205], v[88:91]
	v_mfma_f32_16x16x32_bf16 v[80:83], v[154:157], v[210:213], v[80:83]
	v_mfma_f32_16x16x32_bf16 v[72:75], v[162:165], v[210:213], v[72:75]
	v_mfma_f32_16x16x32_bf16 v[124:127], v[158:161], v[190:193], v[124:127]
	v_mfma_f32_16x16x32_bf16 v[120:123], v[166:169], v[190:193], v[120:123]
	v_mfma_f32_16x16x32_bf16 v[112:115], v[158:161], v[198:201], v[112:115]
	v_mfma_f32_16x16x32_bf16 v[104:107], v[166:169], v[198:201], v[104:107]
	v_mfma_f32_16x16x32_bf16 v[96:99], v[158:161], v[206:209], v[96:99]
	v_mfma_f32_16x16x32_bf16 v[88:91], v[166:169], v[206:209], v[88:91]
	v_mfma_f32_16x16x32_bf16 v[80:83], v[158:161], v[214:217], v[80:83]
	v_mfma_f32_16x16x32_bf16 v[72:75], v[166:169], v[214:217], v[72:75]
	s_setprio 0
	s_setprio 1
	v_mfma_f32_16x16x32_bf16 v[116:119], v[170:173], v[186:189], v[116:119]
	v_mfma_f32_16x16x32_bf16 v[108:111], v[178:181], v[186:189], v[108:111]
	v_mfma_f32_16x16x32_bf16 v[100:103], v[170:173], v[194:197], v[100:103]
	v_mfma_f32_16x16x32_bf16 v[92:95], v[178:181], v[194:197], v[92:95]
	v_mfma_f32_16x16x32_bf16 v[84:87], v[170:173], v[202:205], v[84:87]
	v_mfma_f32_16x16x32_bf16 v[76:79], v[178:181], v[202:205], v[76:79]
	v_mfma_f32_16x16x32_bf16 v[68:71], v[170:173], v[210:213], v[68:71]
	v_mfma_f32_16x16x32_bf16 v[64:67], v[178:181], v[210:213], v[64:67]
	v_mfma_f32_16x16x32_bf16 v[116:119], v[174:177], v[190:193], v[116:119]
	v_mfma_f32_16x16x32_bf16 v[108:111], v[182:185], v[190:193], v[108:111]
	v_mfma_f32_16x16x32_bf16 v[100:103], v[174:177], v[198:201], v[100:103]
	v_mfma_f32_16x16x32_bf16 v[92:95], v[182:185], v[198:201], v[92:95]
	v_mfma_f32_16x16x32_bf16 v[84:87], v[174:177], v[206:209], v[84:87]
	v_mfma_f32_16x16x32_bf16 v[76:79], v[182:185], v[206:209], v[76:79]
	v_mfma_f32_16x16x32_bf16 v[68:71], v[174:177], v[214:217], v[68:71]
	v_mfma_f32_16x16x32_bf16 v[64:67], v[182:185], v[214:217], v[64:67]
	s_setprio 0
	s_barrier
	s_add_i32 s54, s63, s17
	v_lshl_add_u64 v[218:219], v[218:219], 0, s[10:11]
	s_mov_b32 m0, s54
	ds_read_b128 v[186:189], v151 offset:49152
	ds_read_b128 v[190:193], v151 offset:50176
	ds_read_b128 v[194:197], v151 offset:51200
	ds_read_b128 v[198:201], v151 offset:52224
	ds_read_b128 v[202:205], v151 offset:53248
	ds_read_b128 v[206:209], v151 offset:54272
	ds_read_b128 v[210:213], v151 offset:55296
	ds_read_b128 v[214:217], v151 offset:56320
	global_load_lds_dwordx4 v[218:219], off
	s_add_i32 m0, s54, 0x2000
	s_add_u32 s0, s0, 0x40080
	v_lshl_add_u64 v[218:219], v[220:221], 0, s[10:11]
	s_addc_u32 s1, s1, 0
	s_add_i32 s54, s66, s17
	global_load_lds_dwordx4 v[218:219], off
	v_lshl_add_u64 v[218:219], s[0:1], 0, v[132:133]
	s_mov_b32 m0, s54
	s_nop 0
	global_load_lds_dwordx4 v[218:219], off
	v_lshl_add_u64 v[218:219], s[0:1], 0, v[128:129]
	s_add_i32 m0, s54, 0x2000
	s_nop 0
	global_load_lds_dwordx4 v[218:219], off
	v_lshl_add_u64 v[218:219], v[222:223], 0, s[10:11]
	s_mov_b32 m0, s43
	s_nop 0
	global_load_lds_dwordx4 v[218:219], off
	v_lshl_add_u64 v[218:219], v[224:225], 0, s[10:11]
	s_mov_b32 m0, s44
	s_nop 0
	global_load_lds_dwordx4 v[218:219], off
	s_waitcnt vmcnt(8)
	s_waitcnt lgkmcnt(0)
	s_barrier
	s_setprio 1
	s_waitcnt lgkmcnt(0)
	v_mfma_f32_16x16x32_bf16 v[60:63], v[154:157], v[186:189], v[60:63]
	v_mfma_f32_16x16x32_bf16 v[56:59], v[162:165], v[186:189], v[56:59]
	v_mfma_f32_16x16x32_bf16 v[48:51], v[154:157], v[194:197], v[48:51]
	v_mfma_f32_16x16x32_bf16 v[40:43], v[162:165], v[194:197], v[40:43]
	v_mfma_f32_16x16x32_bf16 v[32:35], v[154:157], v[202:205], v[32:35]
	v_mfma_f32_16x16x32_bf16 v[24:27], v[162:165], v[202:205], v[24:27]
	v_mfma_f32_16x16x32_bf16 v[16:19], v[154:157], v[210:213], v[16:19]
	v_mfma_f32_16x16x32_bf16 v[8:11], v[162:165], v[210:213], v[8:11]
	v_mfma_f32_16x16x32_bf16 v[60:63], v[158:161], v[190:193], v[60:63]
	v_mfma_f32_16x16x32_bf16 v[56:59], v[166:169], v[190:193], v[56:59]
	v_mfma_f32_16x16x32_bf16 v[48:51], v[158:161], v[198:201], v[48:51]
	v_mfma_f32_16x16x32_bf16 v[40:43], v[166:169], v[198:201], v[40:43]
	v_mfma_f32_16x16x32_bf16 v[32:35], v[158:161], v[206:209], v[32:35]
	v_mfma_f32_16x16x32_bf16 v[24:27], v[166:169], v[206:209], v[24:27]
	v_mfma_f32_16x16x32_bf16 v[16:19], v[158:161], v[214:217], v[16:19]
	v_mfma_f32_16x16x32_bf16 v[8:11], v[166:169], v[214:217], v[8:11]
	s_setprio 0
	s_setprio 1
	v_mfma_f32_16x16x32_bf16 v[52:55], v[170:173], v[186:189], v[52:55]
	v_mfma_f32_16x16x32_bf16 v[44:47], v[178:181], v[186:189], v[44:47]
	v_mfma_f32_16x16x32_bf16 v[36:39], v[170:173], v[194:197], v[36:39]
	v_mfma_f32_16x16x32_bf16 v[28:31], v[178:181], v[194:197], v[28:31]
	v_mfma_f32_16x16x32_bf16 v[20:23], v[170:173], v[202:205], v[20:23]
	v_mfma_f32_16x16x32_bf16 v[12:15], v[178:181], v[202:205], v[12:15]
	v_mfma_f32_16x16x32_bf16 v[4:7], v[170:173], v[210:213], v[4:7]
	v_mfma_f32_16x16x32_bf16 v[0:3], v[178:181], v[210:213], v[0:3]
	v_mfma_f32_16x16x32_bf16 v[52:55], v[174:177], v[190:193], v[52:55]
	v_mfma_f32_16x16x32_bf16 v[44:47], v[182:185], v[190:193], v[44:47]
	v_mfma_f32_16x16x32_bf16 v[36:39], v[174:177], v[198:201], v[36:39]
	v_mfma_f32_16x16x32_bf16 v[28:31], v[182:185], v[198:201], v[28:31]
	v_mfma_f32_16x16x32_bf16 v[20:23], v[174:177], v[206:209], v[20:23]
	v_mfma_f32_16x16x32_bf16 v[12:15], v[182:185], v[206:209], v[12:15]
	v_mfma_f32_16x16x32_bf16 v[4:7], v[174:177], v[214:217], v[4:7]
	v_mfma_f32_16x16x32_bf16 v[0:3], v[182:185], v[214:217], v[0:3]
	s_setprio 0
	s_barrier
	s_add_i32 s62, s62, 2
	s_add_u32 s48, s48, 0x100
	s_addc_u32 s49, s49, 0
	s_add_u32 s56, s56, 0x100
	s_addc_u32 s57, s57, 0
	s_cmp_gt_u32 s62, 13
	s_cbranch_scc0 .LBB0_217
	s_and_b64 vcc, exec, s[12:13]
	s_cbranch_vccz .LBB0_220
	s_barrier

.LBB0_298:
	v_lshlrev_b32_e32 v0, 1, v234
	v_and_b32_e32 v241, 32, v0
	v_lshlrev_b32_e32 v0, 4, v234
	v_and_b32_e32 v0, 0xc0, v0
	v_lshl_or_b32 v239, v252, 8, v0
	v_add_u32_e32 v0, 0, v241
	v_add3_u32 v248, v0, v238, v239
	v_max3_f32 v0, v18, v19, v2
	v_max3_f32 v36, v20, v21, v3
	s_and_b32 s1, s51, 0x3fffffc0
	v_max3_f32 v0, v0, v4, v5
	v_max3_f32 v36, v36, v24, v25
	s_lshl_b32 s1, s1, 2
	v_max3_f32 v0, v0, v22, v23
	v_max3_f32 v36, v36, v8, v9
	s_add_i32 s45, s1, 0
	v_max3_f32 v0, v0, v6, v7
	v_max3_f32 v36, v36, v28, v29
	s_add_i32 s45, s45, 0x12000
	v_max3_f32 v0, v0, v26, v27
	v_max3_f32 v36, v36, v12, v13
	s_cmp_lg_u32 0, -1
	v_max3_f32 v0, v0, v10, v11
	v_max3_f32 v36, v36, v32, v33
	s_mov_b32 s6, 1
	v_max3_f32 v0, v0, v30, v31
	v_max3_f32 v36, v36, v16, v17
	s_mov_b32 s19, 0
	v_max3_f32 v0, v0, v14, v15
	v_lshlrev_b32_e32 v249, 4, v252
	v_max_f32_e32 v0, v0, v36
	v_lshl_add_u32 v240, v236, 2, s45
	v_mov_b32_e32 v36, v0
	s_nop 1
	v_permlane32_swap_b32_e32 v0, v36
	v_max_f32_e32 v0, v0, v36
	s_nop 0
	v_add_f32_e32 v243, v1, v0
	v_sub_f32_e32 v2, v2, v0
	v_sub_f32_e32 v3, v3, v0
	v_sub_f32_e32 v18, v18, v0
	v_sub_f32_e32 v19, v19, v0
	v_sub_f32_e32 v20, v20, v0
	s_nop 0
	v_xor_b32_e32 v80, 0x80000000, v243
	v_mov_b32_e32 v81, v80
	v_mov_b32_e32 v82, v80
	v_mov_b32_e32 v83, v80
	v_mov_b32_e32 v84, v80
	v_mov_b32_e32 v85, v80
	v_mov_b32_e32 v86, v80
	v_mov_b32_e32 v87, v80
	v_mov_b32_e32 v88, v80
	v_mov_b32_e32 v89, v80
	v_mov_b32_e32 v90, v80
	v_mov_b32_e32 v91, v80
	v_mov_b32_e32 v92, v80
	v_mov_b32_e32 v93, v80
	v_mov_b32_e32 v94, v80
	v_mov_b32_e32 v95, v80
	s_waitcnt vmcnt(0) lgkmcnt(0)
	s_barrier
	v_exp_f32_e32 v96, v2
	v_exp_f32_e32 v97, v3
	v_lshl_add_u64 v[2:3], v[224:225], 0, s[12:13]
	s_mov_b32 s1, m0
	s_mov_b32 m0, s46
	s_nop 0
	global_load_lds_dwordx4 v[2:3], off
	s_mov_b32 m0, s1
	s_cselect_b32 s1, 0, 0
	s_add_i32 s2, s1, s0
	v_lshl_add_u64 v[2:3], v[34:35], 0, s[8:9]
	s_add_i32 s0, s2, 0xa000
	s_mov_b32 s1, m0
	s_mov_b32 m0, s0
	s_nop 0
	global_load_lds_dwordx4 v[2:3], off
	s_mov_b32 m0, s1
	s_mov_b64 s[0:1], 0x20080
	v_lshl_add_u64 v[2:3], v[34:35], 0, s[0:1]
	s_add_i32 s2, s2, 0xc000
	s_mov_b32 s0, m0
	s_mov_b32 m0, s2
	s_nop 0
	global_load_lds_dwordx4 v[2:3], off
	s_mov_b32 m0, s0
	ds_read_b128 v[220:223], v247 offset:8192
	ds_read_b128 v[216:219], v247 offset:8704
	ds_read_b128 v[212:215], v247 offset:10240
	ds_read_b128 v[208:211], v247 offset:10752
	ds_read_b128 v[204:207], v247 offset:12288
	ds_read_b128 v[200:203], v247 offset:12800
	ds_read_b128 v[196:199], v247 offset:14336
	ds_read_b128 v[192:195], v247 offset:14848
	v_sub_f32_e32 v4, v4, v0
	v_sub_f32_e32 v21, v21, v0
	v_sub_f32_e32 v5, v5, v0
	v_sub_f32_e32 v22, v22, v0
	v_sub_f32_e32 v6, v6, v0
	v_sub_f32_e32 v23, v23, v0
	v_sub_f32_e32 v7, v7, v0
	v_sub_f32_e32 v24, v24, v0
	v_sub_f32_e32 v8, v8, v0
	v_sub_f32_e32 v25, v25, v0
	v_sub_f32_e32 v9, v9, v0
	v_sub_f32_e32 v26, v26, v0
	v_sub_f32_e32 v10, v10, v0
	v_sub_f32_e32 v27, v27, v0
	v_sub_f32_e32 v11, v11, v0
	v_sub_f32_e32 v28, v28, v0
	v_sub_f32_e32 v12, v12, v0
	v_sub_f32_e32 v29, v29, v0
	v_sub_f32_e32 v13, v13, v0
	v_sub_f32_e32 v30, v30, v0
	v_sub_f32_e32 v14, v14, v0
	v_sub_f32_e32 v31, v31, v0
	v_sub_f32_e32 v15, v15, v0
	v_sub_f32_e32 v32, v32, v0
	v_sub_f32_e32 v16, v16, v0
	v_sub_f32_e32 v33, v33, v0
	v_sub_f32_e32 v0, v17, v0
	v_exp_f32_e32 v112, v18
	v_exp_f32_e32 v113, v19
	v_exp_f32_e32 v114, v20
	v_exp_f32_e32 v115, v21
	v_exp_f32_e32 v116, v22
	v_exp_f32_e32 v117, v23
	v_exp_f32_e32 v118, v24
	v_exp_f32_e32 v119, v25
	v_exp_f32_e32 v120, v26
	v_exp_f32_e32 v121, v27
	v_exp_f32_e32 v122, v28
	v_exp_f32_e32 v123, v29
	v_exp_f32_e32 v124, v30
	v_exp_f32_e32 v125, v31
	v_exp_f32_e32 v126, v32
	v_exp_f32_e32 v127, v33
	v_exp_f32_e32 v98, v4
	v_exp_f32_e32 v99, v5
	v_exp_f32_e32 v100, v6
	v_exp_f32_e32 v101, v7
	v_exp_f32_e32 v102, v8
	v_exp_f32_e32 v103, v9
	v_exp_f32_e32 v104, v10
	v_exp_f32_e32 v105, v11
	v_exp_f32_e32 v106, v12
	v_exp_f32_e32 v107, v13
	v_exp_f32_e32 v108, v14
	v_exp_f32_e32 v109, v15
	v_exp_f32_e32 v110, v16
	v_exp_f32_e32 v111, v0
	s_waitcnt vmcnt(3) lgkmcnt(0)
	s_barrier
	v_and_b32_e32 v0, 3, v234
	s_andn2_b64 vcc, exec, s[56:57]
	v_cmp_gt_u32_e64 s[2:3], 32, v235
	v_lshlrev_b32_e32 v226, 4, v0
	s_cbranch_vccnz .LBB0_314
	s_lshl_b32 s0, s51, 9
	v_mov_b32_e32 v227, v1
	s_and_b32 s0, s0, 0x18000
	v_lshl_add_u64 v[2:3], s[76:77], 1, v[226:227]
	v_lshl_or_b32 v0, v251, 11, s0
	v_lshl_add_u64 v[2:3], v[2:3], 0, v[0:1]
	v_mov_b32_e32 v14, v1
	v_mov_b32_e32 v15, v1
	v_lshl_add_u64 v[228:229], s[66:67], 0, v[2:3]
	v_readfirstlane_b32 s98, v224
	v_readfirstlane_b32 s99, v225
	s_nop 0
	v_readfirstlane_b32 s100, v228
	v_readfirstlane_b32 s101, v229
	s_nop 1
	v_subrev_u32_e32 v253, s98, v224
	v_subrev_u32_e32 v255, s100, v228
	s_add_u32 s98, s98, 0x80000
	s_addc_u32 s99, s99, 0
	s_add_u32 s100, s100, 0x13040000
	s_addc_u32 s101, s101, 0
	v_mov_b32_e32 v0, v1
	v_mov_b32_e32 v2, v1
	v_mov_b32_e32 v3, v1
	v_mov_b32_e32 v4, v1
	v_mov_b32_e32 v5, v1
	v_mov_b32_e32 v6, v1
	v_mov_b32_e32 v7, v1
	v_mov_b32_e32 v8, v1
	v_mov_b32_e32 v9, v1
	v_mov_b32_e32 v10, v1
	v_mov_b32_e32 v11, v1
	v_mov_b32_e32 v12, v1
	v_mov_b32_e32 v13, v1
	v_mov_b64_e32 v[30:31], v[14:15]
	v_mov_b64_e32 v[46:47], v[14:15]
	v_mov_b64_e32 v[62:63], v[14:15]
	v_mov_b64_e32 v[78:79], v[14:15]
	s_mov_b32 s0, 0
	s_movk_i32 s19, 0x4000
	s_movk_i32 s38, 0x2000
	v_mov_b32_e32 v250, 0
	s_mov_b64 s[72:73], 0
	v_mov_b64_e32 v[28:29], v[12:13]
	v_mov_b64_e32 v[26:27], v[10:11]
	v_mov_b64_e32 v[24:25], v[8:9]
	v_mov_b64_e32 v[22:23], v[6:7]
	v_mov_b64_e32 v[20:21], v[4:5]
	v_mov_b64_e32 v[18:19], v[2:3]
	v_mov_b64_e32 v[16:17], v[0:1]
	v_mov_b64_e32 v[44:45], v[12:13]
	v_mov_b64_e32 v[42:43], v[10:11]
	v_mov_b64_e32 v[40:41], v[8:9]
	v_mov_b64_e32 v[38:39], v[6:7]
	v_mov_b64_e32 v[36:37], v[4:5]
	v_mov_b64_e32 v[34:35], v[2:3]
	v_mov_b64_e32 v[32:33], v[0:1]
	v_mov_b64_e32 v[60:61], v[12:13]
	v_mov_b64_e32 v[58:59], v[10:11]
	v_mov_b64_e32 v[56:57], v[8:9]
	v_mov_b64_e32 v[54:55], v[6:7]
	v_mov_b64_e32 v[52:53], v[4:5]
	v_mov_b64_e32 v[50:51], v[2:3]
	v_mov_b64_e32 v[48:49], v[0:1]
	v_mov_b64_e32 v[76:77], v[12:13]
	v_mov_b64_e32 v[74:75], v[10:11]
	v_mov_b64_e32 v[72:73], v[8:9]
	v_mov_b64_e32 v[70:71], v[6:7]
	v_mov_b64_e32 v[68:69], v[4:5]
	v_mov_b64_e32 v[66:67], v[2:3]
	v_mov_b64_e32 v[64:65], v[0:1]
.LBB0_300:
	s_lshl_b32 s0, s0, 1
	v_add_u32_e32 v0, s0, v248
	ds_read_b64_tr_b16 v[2:3], v0 offset:24576
	ds_read_b64_tr_b16 v[4:5], v0 offset:25088
	s_waitcnt lgkmcnt(9)
	v_mfma_f32_32x32x16_bf16 v[144:159], v[220:223], v[188:191], v[80:95]
	v_add_f32_e32 v6, v112, v113
	v_add_f32_e32 v6, v114, v6
	v_add_f32_e32 v6, v115, v6
	v_add_f32_e32 v6, v116, v6
	v_add_f32_e32 v10, v117, v6
	v_cvt_pk_bf16_f32 v180, v112, v113
	v_cvt_pk_bf16_f32 v181, v114, v115
	ds_read_b64_tr_b16 v[6:7], v0 offset:28672
	ds_read_b64_tr_b16 v[8:9], v0 offset:29184
	s_waitcnt lgkmcnt(10)
	v_mfma_f32_32x32x16_bf16 v[128:143], v[216:219], v[188:191], v[80:95]
	v_add_f32_e32 v10, v118, v10
	v_add_f32_e32 v10, v119, v10
	v_add_f32_e32 v10, v120, v10
	v_add_f32_e32 v14, v121, v10
	v_cvt_pk_bf16_f32 v182, v116, v117
	v_cvt_pk_bf16_f32 v183, v118, v119
	ds_read_b64_tr_b16 v[10:11], v0 offset:25600
	ds_read_b64_tr_b16 v[12:13], v0 offset:26112
	s_waitcnt lgkmcnt(11)
	v_mfma_f32_32x32x16_bf16 v[144:159], v[212:215], v[184:187], v[144:159]
	v_add_f32_e32 v14, v122, v14
	v_add_f32_e32 v14, v123, v14
	v_add_f32_e32 v14, v124, v14
	v_add_f32_e32 v14, v125, v14
	v_cvt_pk_bf16_f32 v172, v120, v121
	v_cvt_pk_bf16_f32 v173, v122, v123
	ds_read_b64_tr_b16 v[112:113], v0 offset:29696
	ds_read_b64_tr_b16 v[114:115], v0 offset:30208
	s_waitcnt lgkmcnt(12)
	v_mfma_f32_32x32x16_bf16 v[128:143], v[208:211], v[184:187], v[128:143]
	v_add_f32_e32 v14, v126, v14
	v_add_f32_e32 v14, v127, v14
	v_add_f32_e32 v14, v96, v14
	v_add_f32_e32 v14, v97, v14
	v_cvt_pk_bf16_f32 v174, v124, v125
	v_cvt_pk_bf16_f32 v175, v126, v127
	ds_read_b64_tr_b16 v[116:117], v0 offset:26624
	ds_read_b64_tr_b16 v[118:119], v0 offset:27136
	s_waitcnt lgkmcnt(13)
	v_mfma_f32_32x32x16_bf16 v[144:159], v[204:207], v[176:179], v[144:159]
	v_add_f32_e32 v14, v98, v14
	v_add_f32_e32 v14, v99, v14
	v_add_f32_e32 v14, v100, v14
	v_add_f32_e32 v14, v101, v14
	v_cvt_pk_bf16_f32 v164, v96, v97
	v_cvt_pk_bf16_f32 v165, v98, v99
	ds_read_b64_tr_b16 v[96:97], v0 offset:30720
	ds_read_b64_tr_b16 v[98:99], v0 offset:31232
	s_waitcnt lgkmcnt(14)
	v_mfma_f32_32x32x16_bf16 v[128:143], v[200:203], v[176:179], v[128:143]
	v_add_f32_e32 v14, v102, v14
	v_add_f32_e32 v14, v103, v14
	v_add_f32_e32 v14, v104, v14
	v_add_f32_e32 v14, v105, v14
	v_cvt_pk_bf16_f32 v166, v100, v101
	v_cvt_pk_bf16_f32 v167, v102, v103
	ds_read_b64_tr_b16 v[100:101], v0 offset:27648
	ds_read_b64_tr_b16 v[102:103], v0 offset:28160
	s_waitcnt lgkmcnt(14)
	v_mfma_f32_32x32x16_bf16 v[144:159], v[196:199], v[168:171], v[144:159]
	v_add_f32_e32 v14, v106, v14
	v_add_f32_e32 v14, v107, v14
	v_add_f32_e32 v14, v108, v14
	v_add_f32_e32 v14, v109, v14
	v_cvt_pk_bf16_f32 v160, v104, v105
	v_cvt_pk_bf16_f32 v161, v106, v107
	ds_read_b64_tr_b16 v[104:105], v0 offset:31744
	ds_read_b64_tr_b16 v[106:107], v0 offset:32256
	v_mfma_f32_32x32x16_bf16 v[128:143], v[192:195], v[168:171], v[128:143]
	v_add_f32_e32 v14, v110, v14
	v_add_f32_e32 v14, v111, v14
	v_add_f32_e32 v214, v250, v14
	v_cvt_pk_bf16_f32 v162, v108, v109
	v_cvt_pk_bf16_f32 v163, v110, v111
	s_add_i32 s0, s38, s46
	s_mov_b32 s1, m0
	s_mov_b32 m0, s0
	s_nop 0
	global_load_lds_dwordx4 v253, s[98:99]
	s_mov_b32 m0, s1
	s_waitcnt lgkmcnt(14)
	v_mfma_f32_32x32x16_bf16 v[16:31], v[180:183], v[2:5], v[16:31]
	s_lshl_b32 s0, s19, 1
	s_add_i32 s0, s0, s47
	s_mov_b32 s1, m0
	s_mov_b32 m0, s0
	s_nop 0
	global_load_lds_dwordx4 v255, s[100:101]
	s_mov_b32 m0, s1
	s_waitcnt lgkmcnt(12)
	v_mfma_f32_32x32x16_bf16 v[32:47], v[180:183], v[6:9], v[32:47]
	s_addk_i32 s0, 0x1f80
	s_mov_b32 s1, m0
	s_mov_b32 m0, s0
	s_nop 0
	global_load_lds_dwordx4 v255, s[100:101] offset:128
	s_mov_b32 m0, s1
	s_add_u32 s98, s98, 0x20000
	s_addc_u32 s99, s99, 0
	s_add_u32 s100, s100, 0x20000
	s_addc_u32 s101, s101, 0
	s_waitcnt lgkmcnt(10)
	v_mfma_f32_32x32x16_bf16 v[16:31], v[172:175], v[10:13], v[16:31]
	v_max_f32_e32 v108, v144, v145
	v_max3_f32 v109, v146, v147, v129
	v_max3_f32 v108, v108, v128, v130
	v_max3_f32 v108, v108, v131, v148
	v_max3_f32 v109, v109, v150, v151
	v_max3_f32 v108, v108, v149, v132
	v_max3_f32 v109, v109, v134, v135
	v_max3_f32 v108, v108, v133, v152
	v_max3_f32 v109, v109, v154, v155
	v_max3_f32 v108, v108, v153, v136
	v_max3_f32 v109, v109, v138, v139
	v_max3_f32 v108, v108, v137, v156
	v_max3_f32 v109, v109, v158, v159
	v_max3_f32 v108, v108, v157, v140
	v_max3_f32 v109, v109, v142, v143
	v_max3_f32 v108, v108, v141, v109
	v_mov_b32_e32 v109, v108
	s_nop 1
	v_permlane32_swap_b32_e32 v108, v109
	v_max_f32_e32 v108, v108, v109
	v_cmp_lt_f32_e32 vcc, s25, v108
	s_cmp_lg_u64 vcc, 0
	s_cselect_b64 s[78:79], -1, 0
	s_cbranch_vccnz .LBB0_308
.LBB0_301:
	v_exp_f32_e32 v144, v144
	v_exp_f32_e32 v145, v145
	ds_read_b64_tr_b16 v[2:3], v0 offset:32768
	ds_read_b64_tr_b16 v[4:5], v0 offset:33280
	v_exp_f32_e32 v146, v146
	v_exp_f32_e32 v147, v147
	ds_read_b64_tr_b16 v[6:7], v0 offset:36864
	ds_read_b64_tr_b16 v[8:9], v0 offset:37376
	v_exp_f32_e32 v148, v148
	v_exp_f32_e32 v149, v149
	ds_read_b64_tr_b16 v[10:11], v0 offset:33792
	ds_read_b64_tr_b16 v[12:13], v0 offset:34304
	s_waitcnt lgkmcnt(14)
	v_mfma_f32_32x32x16_bf16 v[32:47], v[172:175], v[112:115], v[32:47]
	v_exp_f32_e32 v150, v150
	v_exp_f32_e32 v151, v151
	ds_read_b64_tr_b16 v[108:109], v0 offset:37888
	ds_read_b64_tr_b16 v[110:111], v0 offset:38400
	s_waitcnt lgkmcnt(14)
	v_mfma_f32_32x32x16_bf16 v[16:31], v[164:167], v[116:119], v[16:31]
	v_exp_f32_e32 v152, v152
	v_exp_f32_e32 v153, v153
	ds_read_b64_tr_b16 v[112:113], v0 offset:34816
	ds_read_b64_tr_b16 v[114:115], v0 offset:35328
	s_waitcnt lgkmcnt(14)
	v_mfma_f32_32x32x16_bf16 v[32:47], v[164:167], v[96:99], v[32:47]
	v_exp_f32_e32 v154, v154
	v_exp_f32_e32 v155, v155
	ds_read_b64_tr_b16 v[116:117], v0 offset:38912
	ds_read_b64_tr_b16 v[118:119], v0 offset:39424
	s_waitcnt lgkmcnt(14)
	v_mfma_f32_32x32x16_bf16 v[16:31], v[160:163], v[100:103], v[16:31]
	v_exp_f32_e32 v156, v156
	v_exp_f32_e32 v157, v157
	ds_read_b64_tr_b16 v[100:101], v0 offset:35840
	ds_read_b64_tr_b16 v[102:103], v0 offset:36352
	s_waitcnt lgkmcnt(14)
	v_mfma_f32_32x32x16_bf16 v[32:47], v[160:163], v[104:107], v[32:47]
	v_exp_f32_e32 v158, v158
	v_exp_f32_e32 v159, v159
	ds_read_b64_tr_b16 v[104:105], v0 offset:39936
	ds_read_b64_tr_b16 v[106:107], v0 offset:40448
	s_waitcnt lgkmcnt(14)
	v_mfma_f32_32x32x16_bf16 v[48:63], v[180:183], v[2:5], v[48:63]
	v_exp_f32_e32 v128, v128
	v_exp_f32_e32 v129, v129
	s_waitcnt lgkmcnt(12)
	v_mfma_f32_32x32x16_bf16 v[64:79], v[180:183], v[6:9], v[64:79]
	v_exp_f32_e32 v130, v130
	v_exp_f32_e32 v131, v131
	v_add_u32_e32 v0, s19, v247
	ds_read_b128 v[96:99], v0
	ds_read_b128 v[204:207], v0 offset:512
	s_waitcnt lgkmcnt(12)
	v_mfma_f32_32x32x16_bf16 v[48:63], v[172:175], v[10:13], v[48:63]
	v_exp_f32_e32 v132, v132
	v_exp_f32_e32 v133, v133
	ds_read_b128 v[208:211], v0 offset:2048
	ds_read_b128 v[200:203], v0 offset:2560
	s_waitcnt lgkmcnt(12)
	v_mfma_f32_32x32x16_bf16 v[64:79], v[172:175], v[108:111], v[64:79]
	v_exp_f32_e32 v134, v134
	v_exp_f32_e32 v135, v135
	ds_read_b128 v[196:199], v0 offset:4096
	ds_read_b128 v[10:13], v0 offset:4608
	s_waitcnt lgkmcnt(12)
	v_mfma_f32_32x32x16_bf16 v[48:63], v[164:167], v[112:115], v[48:63]
	v_exp_f32_e32 v136, v136
	v_exp_f32_e32 v137, v137
	ds_read_b128 v[6:9], v0 offset:6144
	ds_read_b128 v[2:5], v0 offset:6656
	s_waitcnt lgkmcnt(12)
	v_mfma_f32_32x32x16_bf16 v[64:79], v[164:167], v[116:119], v[64:79]
	v_exp_f32_e32 v138, v138
	v_exp_f32_e32 v139, v139
	s_waitcnt lgkmcnt(10)
	v_mfma_f32_32x32x16_bf16 v[48:63], v[160:163], v[100:103], v[48:63]
	v_exp_f32_e32 v140, v140
	v_exp_f32_e32 v141, v141
	s_waitcnt lgkmcnt(8)
	v_mfma_f32_32x32x16_bf16 v[64:79], v[160:163], v[104:107], v[64:79]
	v_exp_f32_e32 v142, v142
	v_exp_f32_e32 v143, v143
	s_waitcnt vmcnt(3) lgkmcnt(0)
	s_barrier
	s_andn2_b64 vcc, exec, s[78:79]
	v_add_u32_e32 v0, s45, v249
	s_cbranch_vccnz .LBB0_303
	s_waitcnt lgkmcnt(0)
	ds_read_b128 v[100:103], v0 offset:96
	ds_read_b128 v[104:107], v0 offset:64
	ds_read_b128 v[108:111], v0 offset:32
	ds_read_b128 v[112:115], v0
	s_waitcnt lgkmcnt(3)
	v_pk_mul_f32 v[28:29], v[28:29], v[100:101]
	s_waitcnt lgkmcnt(2)
	v_pk_mul_f32 v[24:25], v[24:25], v[104:105]
	s_waitcnt lgkmcnt(1)
	v_pk_mul_f32 v[20:21], v[20:21], v[108:109]
	v_pk_mul_f32 v[30:31], v[30:31], v[102:103]
	v_pk_mul_f32 v[26:27], v[26:27], v[106:107]
	v_pk_mul_f32 v[22:23], v[22:23], v[110:111]
	s_waitcnt lgkmcnt(0)
	v_pk_mul_f32 v[18:19], v[18:19], v[114:115]
	v_pk_mul_f32 v[16:17], v[16:17], v[112:113]
	v_pk_mul_f32 v[44:45], v[44:45], v[100:101]
	v_pk_mul_f32 v[40:41], v[40:41], v[104:105]
	v_pk_mul_f32 v[36:37], v[36:37], v[108:109]
	v_pk_mul_f32 v[46:47], v[46:47], v[102:103]
	v_pk_mul_f32 v[42:43], v[42:43], v[106:107]
	v_pk_mul_f32 v[38:39], v[38:39], v[110:111]
	v_pk_mul_f32 v[34:35], v[34:35], v[114:115]
	v_pk_mul_f32 v[32:33], v[32:33], v[112:113]
	v_pk_mul_f32 v[60:61], v[60:61], v[100:101]
	v_pk_mul_f32 v[56:57], v[56:57], v[104:105]
	v_pk_mul_f32 v[52:53], v[52:53], v[108:109]
	v_pk_mul_f32 v[62:63], v[62:63], v[102:103]
	v_pk_mul_f32 v[58:59], v[58:59], v[106:107]
	v_pk_mul_f32 v[54:55], v[54:55], v[110:111]
	v_pk_mul_f32 v[50:51], v[50:51], v[114:115]
	v_pk_mul_f32 v[48:49], v[48:49], v[112:113]
	v_pk_mul_f32 v[76:77], v[76:77], v[100:101]
	v_pk_mul_f32 v[72:73], v[72:73], v[104:105]
	v_pk_mul_f32 v[68:69], v[68:69], v[108:109]
	v_pk_mul_f32 v[78:79], v[78:79], v[102:103]
	v_pk_mul_f32 v[74:75], v[74:75], v[106:107]
	v_pk_mul_f32 v[70:71], v[70:71], v[110:111]
	v_pk_mul_f32 v[66:67], v[66:67], v[114:115]
	v_pk_mul_f32 v[64:65], v[64:65], v[112:113]
.LBB0_303:
	s_add_i32 s0, s19, 0x2000
	s_cmpk_lg_i32 s19, 0x4000
	s_cselect_b32 s50, s0, 0
	s_lshl_b32 s0, s38, 1
	v_add_u32_e32 v215, s0, v248
	ds_read_b64_tr_b16 v[192:193], v215 offset:24576
	ds_read_b64_tr_b16 v[194:195], v215 offset:25088
	s_waitcnt lgkmcnt(9)
	v_mfma_f32_32x32x16_bf16 v[112:127], v[96:99], v[188:191], v[80:95]
	v_add_f32_e32 v100, v144, v145
	v_add_f32_e32 v100, v146, v100
	v_add_f32_e32 v100, v147, v100
	v_add_f32_e32 v100, v148, v100
	v_add_f32_e32 v100, v149, v100
	v_cvt_pk_bf16_f32 v180, v144, v145
	v_cvt_pk_bf16_f32 v181, v146, v147
	ds_read_b64_tr_b16 v[144:145], v215 offset:28672
	ds_read_b64_tr_b16 v[146:147], v215 offset:29184
	v_add_f32_e32 v96, v150, v100
	v_add_f32_e32 v96, v151, v96
	v_add_f32_e32 v96, v152, v96
	v_add_f32_e32 v160, v153, v96
	s_waitcnt lgkmcnt(10)
	v_mfma_f32_32x32x16_bf16 v[96:111], v[204:207], v[188:191], v[80:95]
	v_cvt_pk_bf16_f32 v182, v148, v149
	v_cvt_pk_bf16_f32 v183, v150, v151
	ds_read_b64_tr_b16 v[148:149], v215 offset:25600
	ds_read_b64_tr_b16 v[150:151], v215 offset:26112
	s_waitcnt lgkmcnt(11)
	v_mfma_f32_32x32x16_bf16 v[112:127], v[208:211], v[184:187], v[112:127]
	v_add_f32_e32 v160, v154, v160
	v_add_f32_e32 v160, v155, v160
	v_add_f32_e32 v160, v156, v160
	v_add_f32_e32 v160, v157, v160
	v_cvt_pk_bf16_f32 v172, v152, v153
	v_cvt_pk_bf16_f32 v173, v154, v155
	ds_read_b64_tr_b16 v[152:153], v215 offset:29696
	ds_read_b64_tr_b16 v[154:155], v215 offset:30208
	s_waitcnt lgkmcnt(12)
	v_mfma_f32_32x32x16_bf16 v[96:111], v[200:203], v[184:187], v[96:111]
	v_add_f32_e32 v160, v158, v160
	v_add_f32_e32 v160, v159, v160
	v_add_f32_e32 v160, v128, v160
	v_add_f32_e32 v160, v129, v160
	v_cvt_pk_bf16_f32 v174, v156, v157
	v_cvt_pk_bf16_f32 v175, v158, v159
	ds_read_b64_tr_b16 v[156:157], v215 offset:26624
	ds_read_b64_tr_b16 v[158:159], v215 offset:27136
	s_waitcnt lgkmcnt(13)
	v_mfma_f32_32x32x16_bf16 v[112:127], v[196:199], v[176:179], v[112:127]
	v_add_f32_e32 v160, v130, v160
	v_add_f32_e32 v160, v131, v160
	v_add_f32_e32 v160, v132, v160
	v_add_f32_e32 v160, v133, v160
	v_cvt_pk_bf16_f32 v164, v128, v129
	v_cvt_pk_bf16_f32 v165, v130, v131
	ds_read_b64_tr_b16 v[128:129], v215 offset:30720
	ds_read_b64_tr_b16 v[130:131], v215 offset:31232
	s_waitcnt lgkmcnt(14)
	v_mfma_f32_32x32x16_bf16 v[96:111], v[10:13], v[176:179], v[96:111]
	v_add_f32_e32 v10, v134, v160
	v_add_f32_e32 v10, v135, v10
	v_add_f32_e32 v10, v136, v10
	v_add_f32_e32 v160, v137, v10
	v_cvt_pk_bf16_f32 v166, v132, v133
	v_cvt_pk_bf16_f32 v167, v134, v135
	ds_read_b64_tr_b16 v[10:11], v215 offset:27648
	ds_read_b64_tr_b16 v[12:13], v215 offset:28160
	s_waitcnt lgkmcnt(14)
	v_mfma_f32_32x32x16_bf16 v[112:127], v[6:9], v[168:171], v[112:127]
	v_add_f32_e32 v6, v138, v160
	v_add_f32_e32 v6, v139, v6
	v_add_f32_e32 v6, v140, v6
	v_add_f32_e32 v132, v141, v6
	v_cvt_pk_bf16_f32 v160, v136, v137
	v_cvt_pk_bf16_f32 v161, v138, v139
	ds_read_b64_tr_b16 v[6:7], v215 offset:31744
	ds_read_b64_tr_b16 v[8:9], v215 offset:32256
	v_mfma_f32_32x32x16_bf16 v[96:111], v[2:5], v[168:171], v[96:111]
	v_add_f32_e32 v2, v142, v132
	v_add_f32_e32 v2, v143, v2
	v_add_f32_e32 v250, v214, v2
	v_cvt_pk_bf16_f32 v162, v140, v141
	v_cvt_pk_bf16_f32 v163, v142, v143
	s_add_i32 s0, s19, s46
	s_mov_b32 s1, m0
	s_mov_b32 m0, s0
	s_nop 0
	global_load_lds_dwordx4 v253, s[98:99]
	s_mov_b32 m0, s1
	s_waitcnt lgkmcnt(14)
	v_mfma_f32_32x32x16_bf16 v[16:31], v[180:183], v[192:195], v[16:31]
	s_lshl_b32 s0, s50, 1
	s_add_i32 s18, s0, s47
	s_mov_b32 s0, m0
	s_mov_b32 m0, s18
	s_nop 0
	global_load_lds_dwordx4 v255, s[100:101]
	s_mov_b32 m0, s0
	s_waitcnt lgkmcnt(12)
	v_mfma_f32_32x32x16_bf16 v[32:47], v[180:183], v[144:147], v[32:47]
	s_add_i32 s0, s18, 0x1f80
	s_mov_b32 s1, m0
	s_mov_b32 m0, s0
	s_nop 0
	global_load_lds_dwordx4 v255, s[100:101] offset:128
	s_mov_b32 m0, s1
	s_add_u32 s98, s98, 0x20000
	s_addc_u32 s99, s99, 0
	s_add_u32 s100, s100, 0x20000
	s_addc_u32 s101, s101, 0
	s_waitcnt lgkmcnt(10)
	v_mfma_f32_32x32x16_bf16 v[16:31], v[172:175], v[148:151], v[16:31]
	v_max_f32_e32 v2, v112, v113
	v_max3_f32 v3, v114, v115, v97
	v_max3_f32 v2, v2, v96, v98
	v_max3_f32 v2, v2, v99, v116
	v_max3_f32 v3, v3, v118, v119
	v_max3_f32 v2, v2, v117, v100
	v_max3_f32 v3, v3, v102, v103
	v_max3_f32 v2, v2, v101, v120
	v_max3_f32 v3, v3, v122, v123
	v_max3_f32 v2, v2, v121, v104
	v_max3_f32 v3, v3, v106, v107
	v_max3_f32 v2, v2, v105, v124
	v_max3_f32 v3, v3, v126, v127
	v_max3_f32 v2, v2, v125, v108
	v_max3_f32 v3, v3, v110, v111
	v_max3_f32 v2, v2, v109, v3
	v_mov_b32_e32 v3, v2
	s_nop 1
	v_permlane32_swap_b32_e32 v2, v3
	v_max_f32_e32 v2, v2, v3
	v_cmp_lt_f32_e32 vcc, s25, v2
	s_cmp_lg_u64 vcc, 0
	s_cselect_b64 s[78:79], -1, 0
	s_cbranch_vccnz .LBB0_311
.LBB0_304:
	v_exp_f32_e32 v112, v112
	v_exp_f32_e32 v113, v113
	ds_read_b64_tr_b16 v[2:3], v215 offset:32768
	ds_read_b64_tr_b16 v[4:5], v215 offset:33280
	v_exp_f32_e32 v114, v114
	v_exp_f32_e32 v115, v115
	ds_read_b64_tr_b16 v[132:133], v215 offset:36864
	ds_read_b64_tr_b16 v[134:135], v215 offset:37376
	v_exp_f32_e32 v116, v116
	v_exp_f32_e32 v117, v117
	ds_read_b64_tr_b16 v[136:137], v215 offset:33792
	ds_read_b64_tr_b16 v[138:139], v215 offset:34304
	s_waitcnt lgkmcnt(14)
	v_mfma_f32_32x32x16_bf16 v[32:47], v[172:175], v[152:155], v[32:47]
	v_exp_f32_e32 v118, v118
	v_exp_f32_e32 v119, v119
	ds_read_b64_tr_b16 v[140:141], v215 offset:37888
	ds_read_b64_tr_b16 v[142:143], v215 offset:38400
	s_waitcnt lgkmcnt(14)
	v_mfma_f32_32x32x16_bf16 v[16:31], v[164:167], v[156:159], v[16:31]
	v_exp_f32_e32 v120, v120
	v_exp_f32_e32 v121, v121
	ds_read_b64_tr_b16 v[144:145], v215 offset:34816
	ds_read_b64_tr_b16 v[146:147], v215 offset:35328
	s_waitcnt lgkmcnt(14)
	v_mfma_f32_32x32x16_bf16 v[32:47], v[164:167], v[128:131], v[32:47]
	v_exp_f32_e32 v122, v122
	v_exp_f32_e32 v123, v123
	ds_read_b64_tr_b16 v[128:129], v215 offset:38912
	ds_read_b64_tr_b16 v[130:131], v215 offset:39424
	s_waitcnt lgkmcnt(14)
	v_mfma_f32_32x32x16_bf16 v[16:31], v[160:163], v[10:13], v[16:31]
	v_exp_f32_e32 v124, v124
	v_exp_f32_e32 v125, v125
	ds_read_b64_tr_b16 v[10:11], v215 offset:35840
	ds_read_b64_tr_b16 v[12:13], v215 offset:36352
	s_waitcnt lgkmcnt(14)
	v_mfma_f32_32x32x16_bf16 v[32:47], v[160:163], v[6:9], v[32:47]
	v_exp_f32_e32 v126, v126
	v_exp_f32_e32 v127, v127
	ds_read_b64_tr_b16 v[6:7], v215 offset:39936
	ds_read_b64_tr_b16 v[8:9], v215 offset:40448
	s_waitcnt lgkmcnt(14)
	v_mfma_f32_32x32x16_bf16 v[48:63], v[180:183], v[2:5], v[48:63]
	v_exp_f32_e32 v96, v96
	v_exp_f32_e32 v97, v97
	s_waitcnt lgkmcnt(12)
	v_mfma_f32_32x32x16_bf16 v[64:79], v[180:183], v[132:135], v[64:79]
	v_exp_f32_e32 v98, v98
	v_exp_f32_e32 v99, v99
	v_add_u32_e32 v2, s50, v247
	ds_read_b128 v[220:223], v2
	ds_read_b128 v[216:219], v2 offset:512
	s_waitcnt lgkmcnt(12)
	v_mfma_f32_32x32x16_bf16 v[48:63], v[172:175], v[136:139], v[48:63]
	v_exp_f32_e32 v100, v100
	v_exp_f32_e32 v101, v101
	ds_read_b128 v[212:215], v2 offset:2048
	ds_read_b128 v[208:211], v2 offset:2560
	s_waitcnt lgkmcnt(12)
	v_mfma_f32_32x32x16_bf16 v[64:79], v[172:175], v[140:143], v[64:79]
	v_exp_f32_e32 v102, v102
	v_exp_f32_e32 v103, v103
	ds_read_b128 v[204:207], v2 offset:4096
	ds_read_b128 v[200:203], v2 offset:4608
	s_waitcnt lgkmcnt(12)
	v_mfma_f32_32x32x16_bf16 v[48:63], v[164:167], v[144:147], v[48:63]
	v_exp_f32_e32 v104, v104
	v_exp_f32_e32 v105, v105
	ds_read_b128 v[196:199], v2 offset:6144
	ds_read_b128 v[192:195], v2 offset:6656
	s_waitcnt lgkmcnt(12)
	v_mfma_f32_32x32x16_bf16 v[64:79], v[164:167], v[128:131], v[64:79]
	v_exp_f32_e32 v106, v106
	v_exp_f32_e32 v107, v107
	s_waitcnt lgkmcnt(10)
	v_mfma_f32_32x32x16_bf16 v[48:63], v[160:163], v[10:13], v[48:63]
	v_exp_f32_e32 v108, v108
	v_exp_f32_e32 v109, v109
	s_waitcnt lgkmcnt(8)
	v_mfma_f32_32x32x16_bf16 v[64:79], v[160:163], v[6:9], v[64:79]
	v_exp_f32_e32 v110, v110
	v_exp_f32_e32 v111, v111
	s_waitcnt vmcnt(3) lgkmcnt(0)
	s_barrier
	s_andn2_b64 vcc, exec, s[78:79]
	s_cbranch_vccnz .LBB0_306
	s_waitcnt lgkmcnt(0)
	ds_read_b128 v[2:5], v0 offset:96
	ds_read_b128 v[6:9], v0 offset:64
	ds_read_b128 v[10:13], v0 offset:32
	ds_read_b128 v[128:131], v0
	s_waitcnt lgkmcnt(3)
	v_pk_mul_f32 v[28:29], v[28:29], v[2:3]
	s_waitcnt lgkmcnt(2)
	v_pk_mul_f32 v[24:25], v[24:25], v[6:7]
	s_waitcnt lgkmcnt(1)
	v_pk_mul_f32 v[20:21], v[20:21], v[10:11]
	v_pk_mul_f32 v[30:31], v[30:31], v[4:5]
	v_pk_mul_f32 v[26:27], v[26:27], v[8:9]
	v_pk_mul_f32 v[22:23], v[22:23], v[12:13]
	s_waitcnt lgkmcnt(0)
	v_pk_mul_f32 v[18:19], v[18:19], v[130:131]
	v_pk_mul_f32 v[16:17], v[16:17], v[128:129]
	v_pk_mul_f32 v[44:45], v[44:45], v[2:3]
	v_pk_mul_f32 v[40:41], v[40:41], v[6:7]
	v_pk_mul_f32 v[36:37], v[36:37], v[10:11]
	v_pk_mul_f32 v[46:47], v[46:47], v[4:5]
	v_pk_mul_f32 v[42:43], v[42:43], v[8:9]
	v_pk_mul_f32 v[38:39], v[38:39], v[12:13]
	v_pk_mul_f32 v[34:35], v[34:35], v[130:131]
	v_pk_mul_f32 v[32:33], v[32:33], v[128:129]
	v_pk_mul_f32 v[60:61], v[60:61], v[2:3]
	v_pk_mul_f32 v[56:57], v[56:57], v[6:7]
	v_pk_mul_f32 v[52:53], v[52:53], v[10:11]
	v_pk_mul_f32 v[62:63], v[62:63], v[4:5]
	v_pk_mul_f32 v[58:59], v[58:59], v[8:9]
	v_pk_mul_f32 v[54:55], v[54:55], v[12:13]
	v_pk_mul_f32 v[50:51], v[50:51], v[130:131]
	v_pk_mul_f32 v[48:49], v[48:49], v[128:129]
	v_pk_mul_f32 v[76:77], v[76:77], v[2:3]
	v_pk_mul_f32 v[72:73], v[72:73], v[6:7]
	v_pk_mul_f32 v[68:69], v[68:69], v[10:11]
	v_pk_mul_f32 v[78:79], v[78:79], v[4:5]
	v_pk_mul_f32 v[74:75], v[74:75], v[8:9]
	v_pk_mul_f32 v[70:71], v[70:71], v[12:13]
	v_pk_mul_f32 v[66:67], v[66:67], v[130:131]
	v_pk_mul_f32 v[64:65], v[64:65], v[128:129]

	.amdhsa_kernel _Z14fwd_megakernel4Args
		.amdhsa_group_segment_fixed_size 0
		.amdhsa_private_segment_fixed_size 0
		.amdhsa_kernarg_size 464
		.amdhsa_user_sgpr_count 2
		.amdhsa_user_sgpr_dispatch_ptr 0
		.amdhsa_user_sgpr_queue_ptr 0
		.amdhsa_user_sgpr_kernarg_segment_ptr 1
		.amdhsa_user_sgpr_dispatch_id 0
		.amdhsa_user_sgpr_kernarg_preload_length 0
		.amdhsa_user_sgpr_kernarg_preload_offset 0
		.amdhsa_user_sgpr_private_segment_size 0
		.amdhsa_uses_dynamic_stack 0
		.amdhsa_enable_private_segment 0
		.amdhsa_system_sgpr_workgroup_id_x 1
		.amdhsa_system_sgpr_workgroup_id_y 0
		.amdhsa_system_sgpr_workgroup_id_z 0
		.amdhsa_system_sgpr_workgroup_info 0
		.amdhsa_system_vgpr_workitem_id 2
		.amdhsa_next_free_vgpr 256
		.amdhsa_next_free_sgpr 102
		.amdhsa_accum_offset 256
		.amdhsa_reserve_vcc 1
		.amdhsa_float_round_mode_32 0
		.amdhsa_float_round_mode_16_64 0
		.amdhsa_float_denorm_mode_32 3
		.amdhsa_float_denorm_mode_16_64 3
		.amdhsa_dx10_clamp 1
		.amdhsa_ieee_mode 1
		.amdhsa_fp16_overflow 0
		.amdhsa_tg_split 0
		.amdhsa_exception_fp_ieee_invalid_op 0
		.amdhsa_exception_fp_denorm_src 0
		.amdhsa_exception_fp_ieee_div_zero 0
		.amdhsa_exception_fp_ieee_overflow 0
		.amdhsa_exception_fp_ieee_underflow 0
		.amdhsa_exception_fp_ieee_inexact 0
		.amdhsa_exception_int_div_zero 0
	.end_amdhsa_kernel

amdhsa.kernels:
  - .agpr_count:     0
    .args:
      - .offset:         0
        .size:           208
        .value_kind:     by_value
      - .offset:         208
        .size:           4
        .value_kind:     hidden_block_count_x
      - .offset:         212
        .size:           4
        .value_kind:     hidden_block_count_y
      - .offset:         216
        .size:           4
        .value_kind:     hidden_block_count_z
      - .offset:         220
        .size:           2
        .value_kind:     hidden_group_size_x
      - .offset:         222
        .size:           2
        .value_kind:     hidden_group_size_y
      - .offset:         224
        .size:           2
        .value_kind:     hidden_group_size_z
      - .offset:         226
        .size:           2
        .value_kind:     hidden_remainder_x
      - .offset:         228
        .size:           2
        .value_kind:     hidden_remainder_y
      - .offset:         230
        .size:           2
        .value_kind:     hidden_remainder_z
      - .offset:         248
        .size:           8
        .value_kind:     hidden_global_offset_x
      - .offset:         256
        .size:           8
        .value_kind:     hidden_global_offset_y
      - .offset:         264
        .size:           8
        .value_kind:     hidden_global_offset_z
      - .offset:         272
        .size:           2
        .value_kind:     hidden_grid_dims
      - .offset:         296
        .size:           8
        .value_kind:     hidden_multigrid_sync_arg
      - .offset:         328
        .size:           4
        .value_kind:     hidden_dynamic_lds_size
    .group_segment_fixed_size: 0
    .kernarg_segment_align: 8
    .kernarg_segment_size: 464
    .language:       OpenCL C
    .language_version:
      - 2
      - 0
    .max_flat_workgroup_size: 512
    .name:           _Z14fwd_megakernel4Args
    .private_segment_fixed_size: 0
    .sgpr_count:     108
    .sgpr_spill_count: 48
    .symbol:         _Z14fwd_megakernel4Args.kd
    .uniform_work_group_size: 1
    .uses_dynamic_stack: false
    .vgpr_count:     256
    .vgpr_spill_count: 0
    .wavefront_size: 64
